# sliding-window attention tile loop: K and V LDS fragment reads batched (8 K frags / 16 V tr-reads in flight, counted lgkmcnt) instead of one read-wait-MFMA at a time
# speedup vs baseline: 1.0035x; 1.0024x over previous
.LBB0_462:
	s_cmp_lt_u32 s98, s33
	s_cselect_b64 s[78:79], -1, 0
	s_cmp_ge_u32 s98, s33
	s_cbranch_scc1 .LBB0_464
	v_add_u32_e32 v224, 0, v236
	ds_read_b128 v[82:85], v224
	ds_read_b128 v[86:89], v224 offset:2080
	ds_read_b128 v[90:93], v224 offset:4160
	ds_read_b128 v[94:97], v224 offset:6240
	ds_read_b128 v[238:241], v224 offset:512
	ds_read_b128 v[242:245], v224 offset:2592
	ds_read_b128 v[246:249], v224 offset:4672
	ds_read_b128 v[154:157], v224 offset:6752
	s_waitcnt lgkmcnt(7)
	v_mfma_f32_32x32x16_bf16 v[66:81], v[82:85], v[150:153], 0
	s_waitcnt lgkmcnt(6)
	v_mfma_f32_32x32x16_bf16 v[66:81], v[86:89], v[146:149], v[66:81]
	s_waitcnt lgkmcnt(5)
	v_mfma_f32_32x32x16_bf16 v[66:81], v[90:93], v[142:145], v[66:81]
	s_waitcnt lgkmcnt(4)
	v_mfma_f32_32x32x16_bf16 v[66:81], v[94:97], v[138:141], v[66:81]
	s_waitcnt lgkmcnt(3)
	v_mfma_f32_32x32x16_bf16 v[82:97], v[238:241], v[150:153], 0
	s_waitcnt lgkmcnt(2)
	v_mfma_f32_32x32x16_bf16 v[82:97], v[242:245], v[146:149], v[82:97]
	s_waitcnt lgkmcnt(1)
	v_mfma_f32_32x32x16_bf16 v[82:97], v[246:249], v[142:145], v[82:97]
	s_waitcnt lgkmcnt(0)
	v_mfma_f32_32x32x16_bf16 v[82:97], v[154:157], v[138:141], v[82:97]

.LBB0_474:
	v_exp_f32_e32 v32, v32
	v_exp_f32_e32 v48, v48
	v_exp_f32_e32 v33, v33
	v_exp_f32_e32 v49, v49
	v_exp_f32_e32 v34, v34
	v_exp_f32_e32 v50, v50
	v_exp_f32_e32 v35, v35
	v_exp_f32_e32 v51, v51
	v_exp_f32_e32 v36, v36
	v_exp_f32_e32 v52, v52
	v_exp_f32_e32 v37, v37
	v_exp_f32_e32 v53, v53
	v_exp_f32_e32 v38, v38
	v_exp_f32_e32 v54, v54
	v_exp_f32_e32 v39, v39
	v_exp_f32_e32 v55, v55
	v_exp_f32_e32 v40, v40
	v_exp_f32_e32 v56, v56
	v_exp_f32_e32 v41, v41
	v_exp_f32_e32 v57, v57
	v_exp_f32_e32 v42, v42
	v_exp_f32_e32 v58, v58
	v_exp_f32_e32 v43, v43
	v_exp_f32_e32 v59, v59
	v_exp_f32_e32 v44, v44
	v_exp_f32_e32 v60, v60
	v_exp_f32_e32 v45, v45
	v_exp_f32_e32 v61, v61
	v_exp_f32_e32 v46, v46
	v_exp_f32_e32 v62, v62
	v_exp_f32_e32 v47, v47
	v_exp_f32_e32 v63, v63
	v_pk_add_f32 v[238:239], v[52:53], v[36:37]
	v_pk_add_f32 v[240:241], v[48:49], v[32:33]
	v_pk_add_f32 v[242:243], v[54:55], v[38:39]
	v_pk_add_f32 v[244:245], v[50:51], v[34:35]
	v_pk_add_f32 v[224:225], v[58:59], v[42:43]
	v_pk_add_f32 v[226:227], v[56:57], v[40:41]
	v_pk_add_f32 v[242:243], v[244:245], v[242:243]
	v_pk_add_f32 v[238:239], v[240:241], v[238:239]
	v_pk_add_f32 v[154:155], v[60:61], v[44:45]
	v_pk_add_f32 v[156:157], v[62:63], v[46:47]
	v_pk_add_f32 v[226:227], v[226:227], v[238:239]
	v_pk_add_f32 v[224:225], v[224:225], v[242:243]
	v_pk_add_f32 v[226:227], v[154:155], v[226:227]
	v_pk_add_f32 v[224:225], v[156:157], v[224:225]
	v_cvt_pk_bf16_f32 v238, v32, v33
	v_pk_mov_b32 v[250:251], v[226:227], v[224:225] op_sel:[1,0]
	v_mov_b32_e32 v227, v225
	v_pk_add_f32 v[224:225], v[250:251], v[226:227]
	v_add_u32_e32 v250, 0, v235
	v_add_f32_e32 v224, v224, v225
	v_cvt_pk_bf16_f32 v239, v34, v35
	v_cvt_pk_bf16_f32 v240, v36, v37
	v_cvt_pk_bf16_f32 v241, v38, v39
	v_add_f32_e32 v165, v165, v224
	v_cvt_pk_bf16_f32 v242, v40, v41
	v_cvt_pk_bf16_f32 v243, v42, v43
	v_cvt_pk_bf16_f32 v244, v44, v45
	v_cvt_pk_bf16_f32 v245, v46, v47
	ds_read_b64_tr_b16 v[32:33], v250 offset:49920
	ds_read_b64_tr_b16 v[34:35], v250 offset:50432
	ds_read_b64_tr_b16 v[36:37], v250 offset:54016
	ds_read_b64_tr_b16 v[38:39], v250 offset:54528
	ds_read_b64_tr_b16 v[40:41], v250 offset:50944
	ds_read_b64_tr_b16 v[42:43], v250 offset:51456
	ds_read_b64_tr_b16 v[44:45], v250 offset:55040
	ds_read_b64_tr_b16 v[46:47], v250 offset:55552
	v_cvt_pk_bf16_f32 v246, v48, v49
	v_cvt_pk_bf16_f32 v247, v50, v51
	v_cvt_pk_bf16_f32 v248, v52, v53
	v_cvt_pk_bf16_f32 v249, v54, v55
	v_cvt_pk_bf16_f32 v154, v56, v57
	v_cvt_pk_bf16_f32 v155, v58, v59
	v_cvt_pk_bf16_f32 v156, v60, v61
	v_cvt_pk_bf16_f32 v157, v62, v63
	ds_read_b64_tr_b16 v[48:49], v250 offset:51968
	ds_read_b64_tr_b16 v[50:51], v250 offset:52480
	ds_read_b64_tr_b16 v[52:53], v250 offset:56064
	ds_read_b64_tr_b16 v[54:55], v250 offset:56576
	s_andn2_b64 vcc, exec, s[78:79]
	s_waitcnt lgkmcnt(10)
	v_mfma_f32_32x32x16_bf16 v[0:15], v[238:241], v[32:35], v[0:15]
	ds_read_b64_tr_b16 v[56:57], v250 offset:52992
	ds_read_b64_tr_b16 v[58:59], v250 offset:53504
	s_waitcnt lgkmcnt(10)
	v_mfma_f32_32x32x16_bf16 v[16:31], v[238:241], v[36:39], v[16:31]
	ds_read_b64_tr_b16 v[60:61], v250 offset:57088
	ds_read_b64_tr_b16 v[62:63], v250 offset:57600
	s_waitcnt lgkmcnt(10)
	v_mfma_f32_32x32x16_bf16 v[0:15], v[242:245], v[40:43], v[0:15]
	s_waitcnt lgkmcnt(8)
	v_mfma_f32_32x32x16_bf16 v[16:31], v[242:245], v[44:47], v[16:31]
	s_waitcnt lgkmcnt(6)
	v_mfma_f32_32x32x16_bf16 v[0:15], v[246:249], v[48:51], v[0:15]
	s_waitcnt lgkmcnt(4)
	v_mfma_f32_32x32x16_bf16 v[16:31], v[246:249], v[52:55], v[16:31]
	s_waitcnt lgkmcnt(2)
	v_mfma_f32_32x32x16_bf16 v[0:15], v[154:157], v[56:59], v[0:15]
	s_waitcnt lgkmcnt(0)
	v_mfma_f32_32x32x16_bf16 v[16:31], v[154:157], v[60:63], v[16:31]
	s_cbranch_vccnz .LBB0_461
	s_add_i32 s98, s98, 2
	s_cmp_gt_u32 s98, s33
	s_cselect_b64 s[78:79], -1, 0
	s_and_b64 vcc, exec, s[78:79]
	s_cbranch_vccnz .LBB0_477
	v_add_u32_e32 v224, 0, v236
	ds_read_b128 v[48:51], v224 offset:8320
	ds_read_b128 v[52:55], v224 offset:10400
	ds_read_b128 v[56:59], v224 offset:12480
	ds_read_b128 v[60:63], v224 offset:14560
	ds_read_b128 v[238:241], v224 offset:8832
	ds_read_b128 v[242:245], v224 offset:10912
	ds_read_b128 v[246:249], v224 offset:12992
	ds_read_b128 v[154:157], v224 offset:15072
	s_waitcnt lgkmcnt(7)
	v_mfma_f32_32x32x16_bf16 v[32:47], v[48:51], v[150:153], 0
	s_waitcnt lgkmcnt(6)
	v_mfma_f32_32x32x16_bf16 v[32:47], v[52:55], v[146:149], v[32:47]
	s_waitcnt lgkmcnt(5)
	v_mfma_f32_32x32x16_bf16 v[32:47], v[56:59], v[142:145], v[32:47]
	s_waitcnt lgkmcnt(4)
	v_mfma_f32_32x32x16_bf16 v[32:47], v[60:63], v[138:141], v[32:47]
	s_waitcnt lgkmcnt(3)
	v_mfma_f32_32x32x16_bf16 v[48:63], v[238:241], v[150:153], 0
	s_waitcnt lgkmcnt(2)
	v_mfma_f32_32x32x16_bf16 v[48:63], v[242:245], v[146:149], v[48:63]
	s_waitcnt lgkmcnt(1)
	v_mfma_f32_32x32x16_bf16 v[48:63], v[246:249], v[142:145], v[48:63]
	s_waitcnt lgkmcnt(0)
	v_mfma_f32_32x32x16_bf16 v[48:63], v[154:157], v[138:141], v[48:63]

.LBB0_487:
	v_exp_f32_e32 v66, v66
	v_exp_f32_e32 v82, v82
	v_exp_f32_e32 v67, v67
	v_exp_f32_e32 v83, v83
	v_exp_f32_e32 v68, v68
	v_exp_f32_e32 v84, v84
	v_exp_f32_e32 v69, v69
	v_exp_f32_e32 v85, v85
	v_exp_f32_e32 v70, v70
	v_exp_f32_e32 v86, v86
	v_exp_f32_e32 v71, v71
	v_exp_f32_e32 v87, v87
	v_exp_f32_e32 v72, v72
	v_exp_f32_e32 v88, v88
	v_exp_f32_e32 v73, v73
	v_exp_f32_e32 v89, v89
	v_exp_f32_e32 v74, v74
	v_exp_f32_e32 v90, v90
	v_exp_f32_e32 v75, v75
	v_exp_f32_e32 v91, v91
	v_exp_f32_e32 v76, v76
	v_exp_f32_e32 v92, v92
	v_exp_f32_e32 v77, v77
	v_exp_f32_e32 v93, v93
	v_exp_f32_e32 v78, v78
	v_exp_f32_e32 v94, v94
	v_exp_f32_e32 v79, v79
	v_exp_f32_e32 v95, v95
	v_exp_f32_e32 v80, v80
	v_exp_f32_e32 v96, v96
	v_exp_f32_e32 v81, v81
	v_exp_f32_e32 v97, v97
	v_pk_add_f32 v[238:239], v[70:71], v[86:87]
	v_pk_add_f32 v[240:241], v[66:67], v[82:83]
	v_pk_add_f32 v[242:243], v[72:73], v[88:89]
	v_pk_add_f32 v[244:245], v[68:69], v[84:85]
	v_pk_add_f32 v[224:225], v[76:77], v[92:93]
	v_pk_add_f32 v[226:227], v[74:75], v[90:91]
	v_pk_add_f32 v[242:243], v[244:245], v[242:243]
	v_pk_add_f32 v[238:239], v[240:241], v[238:239]
	v_pk_add_f32 v[154:155], v[78:79], v[94:95]
	v_pk_add_f32 v[156:157], v[80:81], v[96:97]
	v_pk_add_f32 v[226:227], v[226:227], v[238:239]
	v_pk_add_f32 v[224:225], v[224:225], v[242:243]
	v_pk_add_f32 v[248:249], v[154:155], v[226:227]
	v_pk_add_f32 v[246:247], v[156:157], v[224:225]
	v_cvt_pk_bf16_f32 v224, v66, v67
	v_pk_mov_b32 v[250:251], v[248:249], v[246:247] op_sel:[1,0]
	v_mov_b32_e32 v249, v247
	v_pk_add_f32 v[246:247], v[250:251], v[248:249]
	v_add_u32_e32 v250, 0, v192
	v_add_f32_e32 v246, v246, v247
	v_cvt_pk_bf16_f32 v225, v68, v69
	v_cvt_pk_bf16_f32 v226, v70, v71
	v_cvt_pk_bf16_f32 v227, v72, v73
	v_add_f32_e32 v165, v165, v246
	v_cvt_pk_bf16_f32 v238, v74, v75
	v_cvt_pk_bf16_f32 v239, v76, v77
	v_cvt_pk_bf16_f32 v240, v78, v79
	v_cvt_pk_bf16_f32 v241, v80, v81
	ds_read_b64_tr_b16 v[66:67], v250 offset:49920
	ds_read_b64_tr_b16 v[68:69], v250 offset:50432
	ds_read_b64_tr_b16 v[70:71], v250 offset:54016
	ds_read_b64_tr_b16 v[72:73], v250 offset:54528
	ds_read_b64_tr_b16 v[74:75], v250 offset:50944
	ds_read_b64_tr_b16 v[76:77], v250 offset:51456
	ds_read_b64_tr_b16 v[78:79], v250 offset:55040
	ds_read_b64_tr_b16 v[80:81], v250 offset:55552
	v_cvt_pk_bf16_f32 v242, v82, v83
	v_cvt_pk_bf16_f32 v243, v84, v85
	v_cvt_pk_bf16_f32 v244, v86, v87
	v_cvt_pk_bf16_f32 v245, v88, v89
	v_cvt_pk_bf16_f32 v154, v90, v91
	v_cvt_pk_bf16_f32 v155, v92, v93
	v_cvt_pk_bf16_f32 v156, v94, v95
	v_cvt_pk_bf16_f32 v157, v96, v97
	ds_read_b64_tr_b16 v[82:83], v250 offset:51968
	ds_read_b64_tr_b16 v[84:85], v250 offset:52480
	ds_read_b64_tr_b16 v[86:87], v250 offset:56064
	ds_read_b64_tr_b16 v[88:89], v250 offset:56576
	v_add_u32_e32 v192, 0x4000, v192
	s_addk_i32 s82, 0x80
	v_add_u32_e32 v235, 0x4000, v235
	v_add_u32_e32 v236, 0x4100, v236
	s_waitcnt lgkmcnt(10)
	v_mfma_f32_32x32x16_bf16 v[0:15], v[224:227], v[66:69], v[0:15]
	ds_read_b64_tr_b16 v[90:91], v250 offset:52992
	ds_read_b64_tr_b16 v[92:93], v250 offset:53504
	s_waitcnt lgkmcnt(10)
	v_mfma_f32_32x32x16_bf16 v[16:31], v[224:227], v[70:73], v[16:31]
	ds_read_b64_tr_b16 v[94:95], v250 offset:57088
	ds_read_b64_tr_b16 v[96:97], v250 offset:57600
	s_waitcnt lgkmcnt(10)
	v_mfma_f32_32x32x16_bf16 v[0:15], v[238:241], v[74:77], v[0:15]
	s_waitcnt lgkmcnt(8)
	v_mfma_f32_32x32x16_bf16 v[16:31], v[238:241], v[78:81], v[16:31]
	s_waitcnt lgkmcnt(6)
	v_mfma_f32_32x32x16_bf16 v[0:15], v[242:245], v[82:85], v[0:15]
	s_waitcnt lgkmcnt(4)
	v_mfma_f32_32x32x16_bf16 v[16:31], v[242:245], v[86:89], v[16:31]
	s_waitcnt lgkmcnt(2)
	v_mfma_f32_32x32x16_bf16 v[0:15], v[154:157], v[90:93], v[0:15]
	s_waitcnt lgkmcnt(0)
	v_mfma_f32_32x32x16_bf16 v[16:31], v[154:157], v[94:97], v[16:31]
	s_and_b64 vcc, exec, s[78:79]
	s_cbranch_vccz .LBB0_462
